# Proj (mix-in) epilogue: 8 serialized part-row loads hoisted to the epilogue top (on v45)
# speedup vs baseline: 1.0157x; 1.0068x over previous
.LBB0_256:
	v_lshl_add_u32 v148, s40, 8, v137
	v_ashrrev_i32_e32 v149, 31, v148
	v_lshlrev_b64 v[150:151], 6, v[148:149]
	v_lshl_add_u64 v[152:153], v[142:143], 0, v[150:151]
	global_load_dwordx4 v[196:199], v[152:153], off offset:1024
	global_load_dwordx4 v[200:203], v[152:153], off offset:2048
	global_load_dwordx4 v[204:207], v[152:153], off offset:3072
	v_add_co_u32_e32 v208, vcc, 0x2000, v152
	s_nop 1
	v_addc_co_u32_e32 v209, vcc, 0, v153, vcc
	global_load_dwordx4 v[234:237], v[208:209], off
	global_load_dwordx4 v[238:241], v[208:209], off offset:1024
	global_load_dwordx4 v[222:225], v[208:209], off offset:2048
	global_load_dwordx4 v[208:211], v[208:209], off offset:3072
	global_load_dwordx4 v[152:155], v[152:153], off
	s_cmp_eq_u32 s10, 3
	s_cselect_b64 s[24:25], -1, 0
	s_or_b64 vcc, s[8:9], s[24:25]
	s_cmp_lt_i32 s10, 3
	s_cselect_b64 s[24:25], -1, 0
	s_and_b64 s[24:25], s[24:25], s[14:15]
	s_waitcnt vmcnt(0)
	v_mov_b32_e32 v156, v153
	v_mov_b32_e32 v157, v154
	v_mov_b32_e32 v153, v155
	v_pk_add_f32 v[152:153], v[156:157], v[152:153]
	v_mov_b32_e32 v154, 0x3e38aa3b
	v_add_f32_e32 v152, v152, v153
	ds_bpermute_b32 v153, v169, v152
	v_cndmask_b32_e32 v174, 1.0, v154, vcc
	s_andn2_b64 vcc, exec, s[24:25]
	s_waitcnt lgkmcnt(0)
	v_add_f32_e32 v152, v152, v153
	ds_bpermute_b32 v153, v172, v152
	s_waitcnt lgkmcnt(0)
	v_add_f32_e32 v152, v152, v153
	v_fmamk_f32 v152, v152, 0x3a800000, v216
	v_cmp_gt_f32_e64 s[42:43], s29, v152
	v_mul_f32_e32 v153, 0x4b800000, v152
	s_nop 0
	v_cndmask_b32_e64 v152, v152, v153, s[42:43]
	v_rsq_f32_e32 v152, v152
	v_cndmask_b32_e64 v153, 0, 1, s[24:25]
	v_cmp_ne_u32_e64 s[40:41], 1, v153
	v_mul_f32_e32 v153, 0x45800000, v152
	v_cndmask_b32_e64 v152, v152, v153, s[42:43]
	v_mul_f32_e32 v152, v174, v152
	v_pk_mul_f32 v[126:127], v[126:127], v[152:153] op_sel_hi:[1,0]
	v_pk_mul_f32 v[124:125], v[124:125], v[152:153] op_sel_hi:[1,0]
	v_pk_mul_f32 v[122:123], v[122:123], v[152:153] op_sel_hi:[1,0]
	v_pk_mul_f32 v[120:121], v[120:121], v[152:153] op_sel_hi:[1,0]
	s_cbranch_vccnz .LBB0_260
	ds_bpermute_b32 v170, v169, v124
	ds_bpermute_b32 v156, v169, v120
	ds_bpermute_b32 v171, v169, v125
	ds_bpermute_b32 v157, v169, v121
	ds_bpermute_b32 v158, v169, v126
	ds_bpermute_b32 v154, v169, v122
	ds_bpermute_b32 v159, v169, v127
	ds_bpermute_b32 v155, v169, v123
	s_and_saveexec_b64 s[42:43], s[36:37]
	s_cbranch_execz .LBB0_259
	v_lshl_add_u64 v[162:163], s[20:21], 0, v[150:151]
	global_load_dwordx4 v[176:179], v[162:163], off
	global_load_dwordx4 v[180:183], v[162:163], off offset:32
	global_load_dwordx4 v[184:187], v[162:163], off offset:16
	global_load_dwordx4 v[188:191], v[162:163], off offset:48
	s_waitcnt vmcnt(3)
	v_pk_mul_f32 v[126:127], v[126:127], v[178:179]
	v_pk_mul_f32 v[124:125], v[124:125], v[176:177]
	s_waitcnt vmcnt(2) lgkmcnt(5)
	v_pk_mul_f32 v[162:163], v[180:181], v[170:171]
	s_waitcnt lgkmcnt(1)
	v_pk_mul_f32 v[158:159], v[182:183], v[158:159]
	s_waitcnt vmcnt(1)
	v_pk_mul_f32 v[122:123], v[122:123], v[186:187]
	v_pk_mul_f32 v[120:121], v[120:121], v[184:185]
	s_waitcnt vmcnt(0)
	v_pk_mul_f32 v[156:157], v[188:189], v[156:157]
	s_waitcnt lgkmcnt(0)
	v_pk_mul_f32 v[154:155], v[190:191], v[154:155]
	v_pk_fma_f32 v[126:127], v[140:141], v[158:159], v[126:127]
	v_pk_fma_f32 v[124:125], v[138:139], v[162:163], v[124:125]
	v_pk_fma_f32 v[122:123], v[140:141], v[154:155], v[122:123]
	v_pk_fma_f32 v[120:121], v[138:139], v[156:157], v[120:121]

.LBB0_264:
	v_cvt_pk_bf16_f32 v116, v116, v117
	v_cvt_pk_bf16_f32 v117, v118, v119
	v_cvt_pk_bf16_f32 v119, v114, v115
	v_or_b32_e32 v114, 16, v148
	v_ashrrev_i32_e32 v115, 31, v114
	v_cvt_pk_bf16_f32 v118, v112, v113
	v_lshlrev_b64 v[112:113], 6, v[114:115]
	global_store_dwordx4 v[120:121], v[116:119], off offset:256
	s_and_b64 vcc, exec, s[40:41]
	s_nop 0
	v_lshl_add_u64 v[116:117], v[142:143], 0, v[112:113]
	v_mov_b32_e32 v116, v196
	v_mov_b32_e32 v117, v197
	v_mov_b32_e32 v118, v198
	v_mov_b32_e32 v119, v199
	v_mov_b32_e32 v120, v117
	v_mov_b32_e32 v121, v118
	v_mov_b32_e32 v117, v119
	v_pk_add_f32 v[116:117], v[120:121], v[116:117]
	s_nop 0
	v_add_f32_e32 v116, v116, v117
	ds_bpermute_b32 v117, v169, v116
	s_waitcnt lgkmcnt(0)
	v_add_f32_e32 v116, v116, v117
	ds_bpermute_b32 v117, v172, v116
	s_waitcnt lgkmcnt(0)
	v_add_f32_e32 v116, v116, v117
	v_fmamk_f32 v116, v116, 0x3a800000, v216
	v_mul_f32_e32 v117, 0x4b800000, v116
	v_cmp_gt_f32_e64 s[42:43], s29, v116
	s_nop 1
	v_cndmask_b32_e64 v116, v116, v117, s[42:43]
	v_rsq_f32_e32 v116, v116
	s_nop 0
	v_mul_f32_e32 v117, 0x45800000, v116
	v_cndmask_b32_e64 v116, v116, v117, s[42:43]
	v_mul_f32_e32 v116, v174, v116
	v_pk_mul_f32 v[110:111], v[110:111], v[116:117] op_sel_hi:[1,0]
	v_pk_mul_f32 v[108:109], v[108:109], v[116:117] op_sel_hi:[1,0]
	v_pk_mul_f32 v[106:107], v[106:107], v[116:117] op_sel_hi:[1,0]
	v_pk_mul_f32 v[104:105], v[104:105], v[116:117] op_sel_hi:[1,0]
	s_cbranch_vccnz .LBB0_268
	ds_bpermute_b32 v124, v169, v108
	ds_bpermute_b32 v120, v169, v104
	ds_bpermute_b32 v125, v169, v109
	ds_bpermute_b32 v121, v169, v105
	ds_bpermute_b32 v122, v169, v110
	ds_bpermute_b32 v118, v169, v106
	ds_bpermute_b32 v123, v169, v111
	ds_bpermute_b32 v119, v169, v107
	s_and_saveexec_b64 s[42:43], s[36:37]
	s_cbranch_execz .LBB0_267
	v_lshl_add_u64 v[126:127], s[20:21], 0, v[112:113]
	global_load_dwordx4 v[150:153], v[126:127], off
	global_load_dwordx4 v[154:157], v[126:127], off offset:32
	global_load_dwordx4 v[176:179], v[126:127], off offset:16
	global_load_dwordx4 v[180:183], v[126:127], off offset:48
	s_waitcnt vmcnt(3)
	v_pk_mul_f32 v[110:111], v[110:111], v[152:153]
	v_pk_mul_f32 v[108:109], v[108:109], v[150:151]
	s_waitcnt vmcnt(2) lgkmcnt(5)
	v_pk_mul_f32 v[124:125], v[154:155], v[124:125]
	s_waitcnt lgkmcnt(1)
	v_pk_mul_f32 v[122:123], v[156:157], v[122:123]
	s_waitcnt vmcnt(1)
	v_pk_mul_f32 v[106:107], v[106:107], v[178:179]
	v_pk_mul_f32 v[104:105], v[104:105], v[176:177]
	s_waitcnt vmcnt(0)
	v_pk_mul_f32 v[120:121], v[180:181], v[120:121]
	s_waitcnt lgkmcnt(0)
	v_pk_mul_f32 v[118:119], v[182:183], v[118:119]
	v_pk_fma_f32 v[110:111], v[140:141], v[122:123], v[110:111]
	v_pk_fma_f32 v[108:109], v[138:139], v[124:125], v[108:109]
	v_pk_fma_f32 v[106:107], v[140:141], v[118:119], v[106:107]
	v_pk_fma_f32 v[104:105], v[138:139], v[120:121], v[104:105]

.LBB0_272:
	v_cvt_pk_bf16_f32 v100, v100, v101
	v_cvt_pk_bf16_f32 v101, v102, v103
	v_cvt_pk_bf16_f32 v103, v98, v99
	v_or_b32_e32 v98, 32, v148
	v_ashrrev_i32_e32 v99, 31, v98
	v_cvt_pk_bf16_f32 v102, v96, v97
	v_lshlrev_b64 v[96:97], 6, v[98:99]
	global_store_dwordx4 v[104:105], v[100:103], off offset:256
	s_and_b64 vcc, exec, s[40:41]
	s_nop 0
	v_lshl_add_u64 v[100:101], v[142:143], 0, v[96:97]
	v_mov_b32_e32 v100, v200
	v_mov_b32_e32 v101, v201
	v_mov_b32_e32 v102, v202
	v_mov_b32_e32 v103, v203
	v_mov_b32_e32 v104, v101
	v_mov_b32_e32 v105, v102
	v_mov_b32_e32 v101, v103
	v_pk_add_f32 v[100:101], v[104:105], v[100:101]
	s_nop 0
	v_add_f32_e32 v100, v100, v101
	ds_bpermute_b32 v101, v169, v100
	s_waitcnt lgkmcnt(0)
	v_add_f32_e32 v100, v100, v101
	ds_bpermute_b32 v101, v172, v100
	s_waitcnt lgkmcnt(0)
	v_add_f32_e32 v100, v100, v101
	v_fmamk_f32 v100, v100, 0x3a800000, v216
	v_mul_f32_e32 v101, 0x4b800000, v100
	v_cmp_gt_f32_e64 s[42:43], s29, v100
	s_nop 1
	v_cndmask_b32_e64 v100, v100, v101, s[42:43]
	v_rsq_f32_e32 v100, v100
	s_nop 0
	v_mul_f32_e32 v101, 0x45800000, v100
	v_cndmask_b32_e64 v100, v100, v101, s[42:43]
	v_mul_f32_e32 v100, v174, v100
	v_pk_mul_f32 v[94:95], v[94:95], v[100:101] op_sel_hi:[1,0]
	v_pk_mul_f32 v[92:93], v[92:93], v[100:101] op_sel_hi:[1,0]
	v_pk_mul_f32 v[90:91], v[90:91], v[100:101] op_sel_hi:[1,0]
	v_pk_mul_f32 v[88:89], v[88:89], v[100:101] op_sel_hi:[1,0]
	s_cbranch_vccnz .LBB0_276
	ds_bpermute_b32 v108, v169, v92
	ds_bpermute_b32 v104, v169, v88
	ds_bpermute_b32 v109, v169, v93
	ds_bpermute_b32 v105, v169, v89
	ds_bpermute_b32 v106, v169, v94
	ds_bpermute_b32 v102, v169, v90
	ds_bpermute_b32 v107, v169, v95
	ds_bpermute_b32 v103, v169, v91
	s_and_saveexec_b64 s[42:43], s[36:37]
	s_cbranch_execz .LBB0_275
	v_lshl_add_u64 v[122:123], s[20:21], 0, v[96:97]
	global_load_dwordx4 v[110:113], v[122:123], off
	global_load_dwordx4 v[114:117], v[122:123], off offset:32
	global_load_dwordx4 v[118:121], v[122:123], off offset:16
	s_nop 0
	global_load_dwordx4 v[122:125], v[122:123], off offset:48
	s_waitcnt vmcnt(3)
	v_pk_mul_f32 v[94:95], v[94:95], v[112:113]
	v_pk_mul_f32 v[92:93], v[92:93], v[110:111]
	s_waitcnt vmcnt(2) lgkmcnt(5)
	v_pk_mul_f32 v[108:109], v[114:115], v[108:109]
	s_waitcnt lgkmcnt(1)
	v_pk_mul_f32 v[106:107], v[116:117], v[106:107]
	s_waitcnt vmcnt(1)
	v_pk_mul_f32 v[90:91], v[90:91], v[120:121]
	v_pk_mul_f32 v[88:89], v[88:89], v[118:119]
	s_waitcnt vmcnt(0)
	v_pk_mul_f32 v[104:105], v[122:123], v[104:105]
	s_waitcnt lgkmcnt(0)
	v_pk_mul_f32 v[102:103], v[124:125], v[102:103]
	v_pk_fma_f32 v[94:95], v[140:141], v[106:107], v[94:95]
	v_pk_fma_f32 v[92:93], v[138:139], v[108:109], v[92:93]
	v_pk_fma_f32 v[90:91], v[140:141], v[102:103], v[90:91]
	v_pk_fma_f32 v[88:89], v[138:139], v[104:105], v[88:89]

.LBB0_280:
	v_cvt_pk_bf16_f32 v84, v84, v85
	v_cvt_pk_bf16_f32 v85, v86, v87
	v_cvt_pk_bf16_f32 v87, v82, v83
	v_or_b32_e32 v82, 48, v148
	v_ashrrev_i32_e32 v83, 31, v82
	v_cvt_pk_bf16_f32 v86, v80, v81
	v_lshlrev_b64 v[80:81], 6, v[82:83]
	global_store_dwordx4 v[88:89], v[84:87], off offset:256
	s_and_b64 vcc, exec, s[40:41]
	s_nop 0
	v_lshl_add_u64 v[84:85], v[142:143], 0, v[80:81]
	v_mov_b32_e32 v84, v204
	v_mov_b32_e32 v85, v205
	v_mov_b32_e32 v86, v206
	v_mov_b32_e32 v87, v207
	v_mov_b32_e32 v88, v85
	v_mov_b32_e32 v89, v86
	v_mov_b32_e32 v85, v87
	v_pk_add_f32 v[84:85], v[88:89], v[84:85]
	s_nop 0
	v_add_f32_e32 v84, v84, v85
	ds_bpermute_b32 v85, v169, v84
	s_waitcnt lgkmcnt(0)
	v_add_f32_e32 v84, v84, v85
	ds_bpermute_b32 v85, v172, v84
	s_waitcnt lgkmcnt(0)
	v_add_f32_e32 v84, v84, v85
	v_fmamk_f32 v84, v84, 0x3a800000, v216
	v_mul_f32_e32 v85, 0x4b800000, v84
	v_cmp_gt_f32_e64 s[42:43], s29, v84
	s_nop 1
	v_cndmask_b32_e64 v84, v84, v85, s[42:43]
	v_rsq_f32_e32 v84, v84
	s_nop 0
	v_mul_f32_e32 v85, 0x45800000, v84
	v_cndmask_b32_e64 v84, v84, v85, s[42:43]
	v_mul_f32_e32 v84, v174, v84
	v_pk_mul_f32 v[78:79], v[78:79], v[84:85] op_sel_hi:[1,0]
	v_pk_mul_f32 v[76:77], v[76:77], v[84:85] op_sel_hi:[1,0]
	v_pk_mul_f32 v[74:75], v[74:75], v[84:85] op_sel_hi:[1,0]
	v_pk_mul_f32 v[72:73], v[72:73], v[84:85] op_sel_hi:[1,0]
	s_cbranch_vccnz .LBB0_284
	ds_bpermute_b32 v92, v169, v76
	ds_bpermute_b32 v88, v169, v72
	ds_bpermute_b32 v93, v169, v77
	ds_bpermute_b32 v89, v169, v73
	ds_bpermute_b32 v90, v169, v78
	ds_bpermute_b32 v86, v169, v74
	ds_bpermute_b32 v91, v169, v79
	ds_bpermute_b32 v87, v169, v75
	s_and_saveexec_b64 s[42:43], s[36:37]
	s_cbranch_execz .LBB0_283
	v_lshl_add_u64 v[106:107], s[20:21], 0, v[80:81]
	global_load_dwordx4 v[94:97], v[106:107], off
	global_load_dwordx4 v[98:101], v[106:107], off offset:32
	global_load_dwordx4 v[102:105], v[106:107], off offset:16
	s_nop 0
	global_load_dwordx4 v[106:109], v[106:107], off offset:48
	s_waitcnt vmcnt(3)
	v_pk_mul_f32 v[78:79], v[78:79], v[96:97]
	v_pk_mul_f32 v[76:77], v[76:77], v[94:95]
	s_waitcnt vmcnt(2) lgkmcnt(5)
	v_pk_mul_f32 v[92:93], v[98:99], v[92:93]
	s_waitcnt lgkmcnt(1)
	v_pk_mul_f32 v[90:91], v[100:101], v[90:91]
	s_waitcnt vmcnt(1)
	v_pk_mul_f32 v[74:75], v[74:75], v[104:105]
	v_pk_mul_f32 v[72:73], v[72:73], v[102:103]
	s_waitcnt vmcnt(0)
	v_pk_mul_f32 v[88:89], v[106:107], v[88:89]
	s_waitcnt lgkmcnt(0)
	v_pk_mul_f32 v[86:87], v[108:109], v[86:87]
	v_pk_fma_f32 v[78:79], v[140:141], v[90:91], v[78:79]
	v_pk_fma_f32 v[76:77], v[138:139], v[92:93], v[76:77]
	v_pk_fma_f32 v[74:75], v[140:141], v[86:87], v[74:75]
	v_pk_fma_f32 v[72:73], v[138:139], v[88:89], v[72:73]

.LBB0_288:
	v_cvt_pk_bf16_f32 v68, v68, v69
	v_cvt_pk_bf16_f32 v69, v70, v71
	v_cvt_pk_bf16_f32 v71, v66, v67
	v_add_u32_e32 v66, 0x80, v148
	v_ashrrev_i32_e32 v67, 31, v66
	v_cvt_pk_bf16_f32 v70, v64, v65
	v_lshlrev_b64 v[64:65], 6, v[66:67]
	global_store_dwordx4 v[72:73], v[68:71], off offset:256
	s_and_b64 vcc, exec, s[40:41]
	s_nop 0
	v_lshl_add_u64 v[68:69], v[142:143], 0, v[64:65]
	v_mov_b32_e32 v68, v234
	v_mov_b32_e32 v69, v235
	v_mov_b32_e32 v70, v236
	v_mov_b32_e32 v71, v237
	v_mov_b32_e32 v72, v69
	v_mov_b32_e32 v73, v70
	v_mov_b32_e32 v69, v71
	v_pk_add_f32 v[68:69], v[72:73], v[68:69]
	s_nop 0
	v_add_f32_e32 v68, v68, v69
	ds_bpermute_b32 v69, v169, v68
	s_waitcnt lgkmcnt(0)
	v_add_f32_e32 v68, v68, v69
	ds_bpermute_b32 v69, v172, v68
	s_waitcnt lgkmcnt(0)
	v_add_f32_e32 v68, v68, v69
	v_fmamk_f32 v68, v68, 0x3a800000, v216
	v_mul_f32_e32 v69, 0x4b800000, v68
	v_cmp_gt_f32_e64 s[42:43], s29, v68
	s_nop 1
	v_cndmask_b32_e64 v68, v68, v69, s[42:43]
	v_rsq_f32_e32 v68, v68
	s_nop 0
	v_mul_f32_e32 v69, 0x45800000, v68
	v_cndmask_b32_e64 v68, v68, v69, s[42:43]
	v_mul_f32_e32 v68, v174, v68
	v_pk_mul_f32 v[62:63], v[62:63], v[68:69] op_sel_hi:[1,0]
	v_pk_mul_f32 v[60:61], v[60:61], v[68:69] op_sel_hi:[1,0]
	v_pk_mul_f32 v[58:59], v[58:59], v[68:69] op_sel_hi:[1,0]
	v_pk_mul_f32 v[56:57], v[56:57], v[68:69] op_sel_hi:[1,0]
	s_cbranch_vccnz .LBB0_292
	ds_bpermute_b32 v76, v169, v60
	ds_bpermute_b32 v72, v169, v56
	ds_bpermute_b32 v77, v169, v61
	ds_bpermute_b32 v73, v169, v57
	ds_bpermute_b32 v74, v169, v62
	ds_bpermute_b32 v70, v169, v58
	ds_bpermute_b32 v75, v169, v63
	ds_bpermute_b32 v71, v169, v59
	s_and_saveexec_b64 s[42:43], s[36:37]
	s_cbranch_execz .LBB0_291
	v_lshl_add_u64 v[90:91], s[20:21], 0, v[64:65]
	global_load_dwordx4 v[78:81], v[90:91], off
	global_load_dwordx4 v[82:85], v[90:91], off offset:32
	global_load_dwordx4 v[86:89], v[90:91], off offset:16
	s_nop 0
	global_load_dwordx4 v[90:93], v[90:91], off offset:48
	s_waitcnt vmcnt(3)
	v_pk_mul_f32 v[62:63], v[62:63], v[80:81]
	v_pk_mul_f32 v[60:61], v[60:61], v[78:79]
	s_waitcnt vmcnt(2) lgkmcnt(5)
	v_pk_mul_f32 v[76:77], v[82:83], v[76:77]
	s_waitcnt lgkmcnt(1)
	v_pk_mul_f32 v[74:75], v[84:85], v[74:75]
	s_waitcnt vmcnt(1)
	v_pk_mul_f32 v[58:59], v[58:59], v[88:89]
	v_pk_mul_f32 v[56:57], v[56:57], v[86:87]
	s_waitcnt vmcnt(0)
	v_pk_mul_f32 v[72:73], v[90:91], v[72:73]
	s_waitcnt lgkmcnt(0)
	v_pk_mul_f32 v[70:71], v[92:93], v[70:71]
	v_pk_fma_f32 v[62:63], v[140:141], v[74:75], v[62:63]
	v_pk_fma_f32 v[60:61], v[138:139], v[76:77], v[60:61]
	v_pk_fma_f32 v[58:59], v[140:141], v[70:71], v[58:59]
	v_pk_fma_f32 v[56:57], v[138:139], v[72:73], v[56:57]

.LBB0_296:
	v_cvt_pk_bf16_f32 v52, v52, v53
	v_cvt_pk_bf16_f32 v53, v54, v55
	v_cvt_pk_bf16_f32 v55, v50, v51
	v_add_u32_e32 v50, 0x90, v148
	v_ashrrev_i32_e32 v51, 31, v50
	v_cvt_pk_bf16_f32 v54, v48, v49
	v_lshlrev_b64 v[48:49], 6, v[50:51]
	global_store_dwordx4 v[56:57], v[52:55], off offset:256
	s_and_b64 vcc, exec, s[40:41]
	s_nop 0
	v_lshl_add_u64 v[52:53], v[142:143], 0, v[48:49]
	v_mov_b32_e32 v52, v238
	v_mov_b32_e32 v53, v239
	v_mov_b32_e32 v54, v240
	v_mov_b32_e32 v55, v241
	v_mov_b32_e32 v56, v53
	v_mov_b32_e32 v57, v54
	v_mov_b32_e32 v53, v55
	v_pk_add_f32 v[52:53], v[56:57], v[52:53]
	s_nop 0
	v_add_f32_e32 v52, v52, v53
	ds_bpermute_b32 v53, v169, v52
	s_waitcnt lgkmcnt(0)
	v_add_f32_e32 v52, v52, v53
	ds_bpermute_b32 v53, v172, v52
	s_waitcnt lgkmcnt(0)
	v_add_f32_e32 v52, v52, v53
	v_fmamk_f32 v52, v52, 0x3a800000, v216
	v_mul_f32_e32 v53, 0x4b800000, v52
	v_cmp_gt_f32_e64 s[42:43], s29, v52
	s_nop 1
	v_cndmask_b32_e64 v52, v52, v53, s[42:43]
	v_rsq_f32_e32 v52, v52
	s_nop 0
	v_mul_f32_e32 v53, 0x45800000, v52
	v_cndmask_b32_e64 v52, v52, v53, s[42:43]
	v_mul_f32_e32 v52, v174, v52
	v_pk_mul_f32 v[46:47], v[46:47], v[52:53] op_sel_hi:[1,0]
	v_pk_mul_f32 v[44:45], v[44:45], v[52:53] op_sel_hi:[1,0]
	v_pk_mul_f32 v[42:43], v[42:43], v[52:53] op_sel_hi:[1,0]
	v_pk_mul_f32 v[40:41], v[40:41], v[52:53] op_sel_hi:[1,0]
	s_cbranch_vccnz .LBB0_300
	ds_bpermute_b32 v60, v169, v44
	ds_bpermute_b32 v56, v169, v40
	ds_bpermute_b32 v61, v169, v45
	ds_bpermute_b32 v57, v169, v41
	ds_bpermute_b32 v58, v169, v46
	ds_bpermute_b32 v54, v169, v42
	ds_bpermute_b32 v59, v169, v47
	ds_bpermute_b32 v55, v169, v43
	s_and_saveexec_b64 s[42:43], s[36:37]
	s_cbranch_execz .LBB0_299
	v_lshl_add_u64 v[74:75], s[20:21], 0, v[48:49]
	global_load_dwordx4 v[62:65], v[74:75], off
	global_load_dwordx4 v[66:69], v[74:75], off offset:32
	global_load_dwordx4 v[70:73], v[74:75], off offset:16
	s_nop 0
	global_load_dwordx4 v[74:77], v[74:75], off offset:48
	s_waitcnt vmcnt(3)
	v_pk_mul_f32 v[46:47], v[46:47], v[64:65]
	v_pk_mul_f32 v[44:45], v[44:45], v[62:63]
	s_waitcnt vmcnt(2) lgkmcnt(5)
	v_pk_mul_f32 v[60:61], v[66:67], v[60:61]
	s_waitcnt lgkmcnt(1)
	v_pk_mul_f32 v[58:59], v[68:69], v[58:59]
	s_waitcnt vmcnt(1)
	v_pk_mul_f32 v[42:43], v[42:43], v[72:73]
	v_pk_mul_f32 v[40:41], v[40:41], v[70:71]
	s_waitcnt vmcnt(0)
	v_pk_mul_f32 v[56:57], v[74:75], v[56:57]
	s_waitcnt lgkmcnt(0)
	v_pk_mul_f32 v[54:55], v[76:77], v[54:55]
	v_pk_fma_f32 v[46:47], v[140:141], v[58:59], v[46:47]
	v_pk_fma_f32 v[44:45], v[138:139], v[60:61], v[44:45]
	v_pk_fma_f32 v[42:43], v[140:141], v[54:55], v[42:43]
	v_pk_fma_f32 v[40:41], v[138:139], v[56:57], v[40:41]

.LBB0_304:
	v_cvt_pk_bf16_f32 v36, v36, v37
	v_cvt_pk_bf16_f32 v37, v38, v39
	v_cvt_pk_bf16_f32 v39, v34, v35
	v_add_u32_e32 v34, 0xa0, v148
	v_ashrrev_i32_e32 v35, 31, v34
	v_cvt_pk_bf16_f32 v38, v32, v33
	v_lshlrev_b64 v[32:33], 6, v[34:35]
	global_store_dwordx4 v[40:41], v[36:39], off offset:256
	s_and_b64 vcc, exec, s[40:41]
	s_nop 0
	v_lshl_add_u64 v[36:37], v[142:143], 0, v[32:33]
	v_mov_b32_e32 v36, v222
	v_mov_b32_e32 v37, v223
	v_mov_b32_e32 v38, v224
	v_mov_b32_e32 v39, v225
	v_mov_b32_e32 v40, v37
	v_mov_b32_e32 v41, v38
	v_mov_b32_e32 v37, v39
	v_pk_add_f32 v[36:37], v[40:41], v[36:37]
	s_nop 0
	v_add_f32_e32 v36, v36, v37
	ds_bpermute_b32 v37, v169, v36
	s_waitcnt lgkmcnt(0)
	v_add_f32_e32 v36, v36, v37
	ds_bpermute_b32 v37, v172, v36
	s_waitcnt lgkmcnt(0)
	v_add_f32_e32 v36, v36, v37
	v_fmamk_f32 v36, v36, 0x3a800000, v216
	v_mul_f32_e32 v37, 0x4b800000, v36
	v_cmp_gt_f32_e64 s[42:43], s29, v36
	s_nop 1
	v_cndmask_b32_e64 v36, v36, v37, s[42:43]
	v_rsq_f32_e32 v36, v36
	s_nop 0
	v_mul_f32_e32 v37, 0x45800000, v36
	v_cndmask_b32_e64 v36, v36, v37, s[42:43]
	v_mul_f32_e32 v36, v174, v36
	v_pk_mul_f32 v[30:31], v[30:31], v[36:37] op_sel_hi:[1,0]
	v_pk_mul_f32 v[28:29], v[28:29], v[36:37] op_sel_hi:[1,0]
	v_pk_mul_f32 v[26:27], v[26:27], v[36:37] op_sel_hi:[1,0]
	v_pk_mul_f32 v[24:25], v[24:25], v[36:37] op_sel_hi:[1,0]
	s_cbranch_vccnz .LBB0_308
	ds_bpermute_b32 v44, v169, v28
	ds_bpermute_b32 v40, v169, v24
	ds_bpermute_b32 v45, v169, v29
	ds_bpermute_b32 v41, v169, v25
	ds_bpermute_b32 v42, v169, v30
	ds_bpermute_b32 v38, v169, v26
	ds_bpermute_b32 v43, v169, v31
	ds_bpermute_b32 v39, v169, v27
	s_and_saveexec_b64 s[42:43], s[36:37]
	s_cbranch_execz .LBB0_307
	v_lshl_add_u64 v[58:59], s[20:21], 0, v[32:33]
	global_load_dwordx4 v[46:49], v[58:59], off
	global_load_dwordx4 v[50:53], v[58:59], off offset:32
	global_load_dwordx4 v[54:57], v[58:59], off offset:16
	s_nop 0
	global_load_dwordx4 v[58:61], v[58:59], off offset:48
	s_waitcnt vmcnt(3)
	v_pk_mul_f32 v[30:31], v[30:31], v[48:49]
	v_pk_mul_f32 v[28:29], v[28:29], v[46:47]
	s_waitcnt vmcnt(2) lgkmcnt(5)
	v_pk_mul_f32 v[44:45], v[50:51], v[44:45]
	s_waitcnt lgkmcnt(1)
	v_pk_mul_f32 v[42:43], v[52:53], v[42:43]
	s_waitcnt vmcnt(1)
	v_pk_mul_f32 v[26:27], v[26:27], v[56:57]
	v_pk_mul_f32 v[24:25], v[24:25], v[54:55]
	s_waitcnt vmcnt(0)
	v_pk_mul_f32 v[40:41], v[58:59], v[40:41]
	s_waitcnt lgkmcnt(0)
	v_pk_mul_f32 v[38:39], v[60:61], v[38:39]
	v_pk_fma_f32 v[30:31], v[140:141], v[42:43], v[30:31]
	v_pk_fma_f32 v[28:29], v[138:139], v[44:45], v[28:29]
	v_pk_fma_f32 v[26:27], v[140:141], v[38:39], v[26:27]
	v_pk_fma_f32 v[24:25], v[138:139], v[40:41], v[24:25]

.LBB0_312:
	v_cvt_pk_bf16_f32 v20, v20, v21
	v_cvt_pk_bf16_f32 v21, v22, v23
	v_cvt_pk_bf16_f32 v23, v18, v19
	v_add_u32_e32 v18, 0xb0, v148
	v_ashrrev_i32_e32 v19, 31, v18
	v_cvt_pk_bf16_f32 v22, v16, v17
	v_lshlrev_b64 v[16:17], 6, v[18:19]
	global_store_dwordx4 v[24:25], v[20:23], off offset:256
	s_and_b64 vcc, exec, s[40:41]
	s_nop 0
	v_lshl_add_u64 v[20:21], v[142:143], 0, v[16:17]
	v_mov_b32_e32 v20, v208
	v_mov_b32_e32 v21, v209
	v_mov_b32_e32 v22, v210
	v_mov_b32_e32 v23, v211
	v_mov_b32_e32 v24, v21
	v_mov_b32_e32 v25, v22
	v_mov_b32_e32 v21, v23
	v_pk_add_f32 v[20:21], v[24:25], v[20:21]
	s_nop 0
	v_add_f32_e32 v20, v20, v21
	ds_bpermute_b32 v21, v169, v20
	s_waitcnt lgkmcnt(0)
	v_add_f32_e32 v20, v20, v21
	ds_bpermute_b32 v21, v172, v20
	s_waitcnt lgkmcnt(0)
	v_add_f32_e32 v20, v20, v21
	v_fmamk_f32 v20, v20, 0x3a800000, v216
	v_mul_f32_e32 v21, 0x4b800000, v20
	v_cmp_gt_f32_e64 s[42:43], s29, v20
	s_nop 1
	v_cndmask_b32_e64 v20, v20, v21, s[42:43]
	v_rsq_f32_e32 v20, v20
	s_nop 0
	v_mul_f32_e32 v21, 0x45800000, v20
	v_cndmask_b32_e64 v20, v20, v21, s[42:43]
	v_mul_f32_e32 v20, v174, v20
	v_pk_mul_f32 v[14:15], v[14:15], v[20:21] op_sel_hi:[1,0]
	v_pk_mul_f32 v[12:13], v[12:13], v[20:21] op_sel_hi:[1,0]
	v_pk_mul_f32 v[10:11], v[10:11], v[20:21] op_sel_hi:[1,0]
	v_pk_mul_f32 v[8:9], v[8:9], v[20:21] op_sel_hi:[1,0]
	s_cbranch_vccnz .LBB0_316
	ds_bpermute_b32 v28, v169, v12
	ds_bpermute_b32 v24, v169, v8
	ds_bpermute_b32 v29, v169, v13
	ds_bpermute_b32 v25, v169, v9
	ds_bpermute_b32 v26, v169, v14
	ds_bpermute_b32 v22, v169, v10
	ds_bpermute_b32 v27, v169, v15
	ds_bpermute_b32 v23, v169, v11
	s_and_saveexec_b64 s[42:43], s[36:37]
	s_cbranch_execz .LBB0_315
	v_lshl_add_u64 v[42:43], s[20:21], 0, v[16:17]
	global_load_dwordx4 v[30:33], v[42:43], off
	global_load_dwordx4 v[34:37], v[42:43], off offset:32
	global_load_dwordx4 v[38:41], v[42:43], off offset:16
	s_nop 0
	global_load_dwordx4 v[42:45], v[42:43], off offset:48
	s_waitcnt vmcnt(3)
	v_pk_mul_f32 v[14:15], v[14:15], v[32:33]
	v_pk_mul_f32 v[12:13], v[12:13], v[30:31]
	s_waitcnt vmcnt(2) lgkmcnt(5)
	v_pk_mul_f32 v[28:29], v[34:35], v[28:29]
	s_waitcnt lgkmcnt(1)
	v_pk_mul_f32 v[26:27], v[36:37], v[26:27]
	s_waitcnt vmcnt(1)
	v_pk_mul_f32 v[10:11], v[10:11], v[40:41]
	v_pk_mul_f32 v[8:9], v[8:9], v[38:39]
	s_waitcnt vmcnt(0)
	v_pk_mul_f32 v[24:25], v[42:43], v[24:25]
	s_waitcnt lgkmcnt(0)
	v_pk_mul_f32 v[22:23], v[44:45], v[22:23]
	v_pk_fma_f32 v[14:15], v[140:141], v[26:27], v[14:15]
	v_pk_fma_f32 v[12:13], v[138:139], v[28:29], v[12:13]
	v_pk_fma_f32 v[10:11], v[140:141], v[22:23], v[10:11]
	v_pk_fma_f32 v[8:9], v[138:139], v[24:25], v[8:9]
